# ssc units (sample indexer scores): the 4 k-step load pairs per tile were serialized behind vmcnt(0); all 8 loads issued together with counted waits (both layers); on comb13
# speedup vs baseline: 1.0005x; 1.0005x over previous
; __device__ __forceinline__ void ssc_unit(const Ctx& c, int l, int sb, int ksp) {
;     ...
;         for (int i = 0; i < 4; ++i) {
;             const int s0 = ksp * 1024 + (c.wave + 8 * i) * 32;
;             const int page = ptab[s0 >> 7];
;             const float* kp = c.f(I_CKI) + (((size_t)l * NPOOL + page) * 128 + (s0 & 127) + n) * 64 + 8 * hf;
;             f32x16 acc;
; #pragma unroll
;             for (int v = 0; v < 16; ++v) acc[v] = 0.f;
; #pragma unroll
;             for (int ks = 0; ks < 4; ++ks) {
;                 const f32x4 k0 = *(const f32x4*)(kp + 16 * ks), k1 = *(const f32x4*)(kp + 16 * ks + 4);
;                 acc = __builtin_amdgcn_mfma_f32_32x32x16_bf16(Af[ks], pack8(k0, k1), acc, 0, 0, 0);
;             }
;             float sc = 0.f;
; #pragma unroll
;             for (int v = 0; v < 16; ++v) sc += wq[v] * fmaxf(acc[v], 0.f);
;             SCS[(size_t)(2 * pr + hf) * SCS_LD + s0 + n] = sc;
;         }
;     }
;     if (ksp == 15 && c.wave == 0 && lane < 16) {
.LBB0_1093:
	s_add_i32 s8, s16, s18
	s_ashr_i32 s20, s8, 7
	s_ashr_i32 s21, s20, 31
	s_lshl_b64 s[20:21], s[20:21], 2
	s_add_u32 s20, s14, s20
	s_addc_u32 s21, s15, s21
	global_load_dword v0, v17, s[20:21]
	s_ashr_i32 s9, s8, 31
	s_addk_i32 s18, 0x100
	s_cmpk_eq_i32 s18, 0x400
	s_waitcnt vmcnt(0)
	v_ashrrev_i32_e32 v1, 31, v0
	v_lshlrev_b64 v[0:1], 15, v[0:1]
	v_lshl_add_u64 v[76:77], v[38:39], 0, v[0:1]
	global_load_dwordx4 v[0:3], v[76:77], off offset:16
	global_load_dwordx4 v[4:7], v[76:77], off
	global_load_dwordx4 v[68:71], v[76:77], off offset:80
	global_load_dwordx4 v[72:75], v[76:77], off offset:64
	global_load_dwordx4 v[80:83], v[76:77], off offset:144
	global_load_dwordx4 v[84:87], v[76:77], off offset:128
	global_load_dwordx4 v[88:91], v[76:77], off offset:208
	global_load_dwordx4 v[92:95], v[76:77], off offset:192
	s_waitcnt vmcnt(6)
	v_cvt_pk_bf16_f32 v4, v4, v5
	v_cvt_pk_bf16_f32 v5, v6, v7
	v_cvt_pk_bf16_f32 v6, v0, v1
	v_cvt_pk_bf16_f32 v7, v2, v3
	s_nop 1
	v_mfma_f32_32x32x16_bf16 v[0:15], v[18:21], v[4:7], 0
	s_waitcnt vmcnt(4)
	v_cvt_pk_bf16_f32 v72, v72, v73
	v_cvt_pk_bf16_f32 v73, v74, v75
	v_cvt_pk_bf16_f32 v74, v68, v69
	v_cvt_pk_bf16_f32 v75, v70, v71
	s_nop 1
	v_mfma_f32_32x32x16_bf16 v[0:15], v[22:25], v[72:75], v[0:15]
	s_waitcnt vmcnt(2)
	v_cvt_pk_bf16_f32 v84, v84, v85
	v_cvt_pk_bf16_f32 v85, v86, v87
	v_cvt_pk_bf16_f32 v86, v80, v81
	v_cvt_pk_bf16_f32 v87, v82, v83
	s_nop 1
	v_mfma_f32_32x32x16_bf16 v[0:15], v[26:29], v[84:87], v[0:15]
	s_waitcnt vmcnt(0)
	v_cvt_pk_bf16_f32 v92, v92, v93
	v_cvt_pk_bf16_f32 v93, v94, v95
	v_cvt_pk_bf16_f32 v94, v88, v89
	v_cvt_pk_bf16_f32 v95, v90, v91
	s_nop 1
	v_mfma_f32_32x32x16_bf16 v[0:15], v[30:33], v[92:95], v[0:15]
	s_nop 11
	v_max_f32_e32 v0, v0, v0
	v_max_f32_e32 v0, 0, v0
	v_fma_f32 v61, v16, v0, 0
	v_max_f32_e32 v0, v1, v1
	v_max_f32_e32 v0, 0, v0
	v_fmac_f32_e32 v61, v58, v0
	v_max_f32_e32 v0, v2, v2
	v_max_f32_e32 v0, 0, v0
	v_fmac_f32_e32 v61, v59, v0
	v_max_f32_e32 v0, v3, v3
	v_max_f32_e32 v0, 0, v0
	v_fmac_f32_e32 v61, v60, v0
	v_max_f32_e32 v0, v4, v4
	v_max_f32_e32 v1, v5, v5
	v_max_f32_e32 v0, 0, v0
	v_max_f32_e32 v1, 0, v1
	v_pk_mul_f32 v[0:1], v[40:41], v[0:1]
	s_nop 0
	v_add_f32_e32 v0, v0, v61
	v_add_f32_e32 v2, v1, v0
	v_max_f32_e32 v0, v6, v6
	v_max_f32_e32 v1, v7, v7
	v_max_f32_e32 v0, 0, v0
	v_max_f32_e32 v1, 0, v1
	v_pk_mul_f32 v[0:1], v[42:43], v[0:1]
	s_nop 0
	v_add_f32_e32 v0, v0, v2
	v_add_f32_e32 v2, v1, v0
	v_max_f32_e32 v0, v8, v8
	v_max_f32_e32 v1, v9, v9
	v_max_f32_e32 v0, 0, v0
	v_max_f32_e32 v1, 0, v1
	v_pk_mul_f32 v[0:1], v[44:45], v[0:1]
	s_nop 0
	v_add_f32_e32 v0, v0, v2
	v_add_f32_e32 v2, v1, v0
	v_max_f32_e32 v0, v10, v10
	v_max_f32_e32 v1, v11, v11
	v_max_f32_e32 v0, 0, v0
	v_max_f32_e32 v1, 0, v1
	v_pk_mul_f32 v[0:1], v[46:47], v[0:1]
	s_nop 0
	v_add_f32_e32 v0, v0, v2
	v_add_f32_e32 v2, v1, v0
	v_max_f32_e32 v0, v12, v12
	v_max_f32_e32 v1, v13, v13
	v_max_f32_e32 v0, 0, v0
	v_max_f32_e32 v1, 0, v1
	v_pk_mul_f32 v[0:1], v[48:49], v[0:1]
	s_nop 0
	v_add_f32_e32 v0, v0, v2
	v_add_f32_e32 v2, v1, v0
	v_max_f32_e32 v0, v14, v14
	v_max_f32_e32 v1, v15, v15
	v_max_f32_e32 v0, 0, v0
	v_max_f32_e32 v1, 0, v1
	v_pk_mul_f32 v[0:1], v[50:51], v[0:1]
	s_nop 0
	v_add_f32_e32 v0, v0, v2
	v_add_f32_e32 v2, v1, v0
	v_lshl_add_u64 v[0:1], s[8:9], 2, v[52:53]
	global_store_dword v[0:1], v2, off
	s_cbranch_scc0 .LBB0_1093
	s_mov_b32 s18, 2
	s_mov_b64 s[8:9], 0
	s_and_b64 vcc, exec, s[6:7]
	s_cbranch_vccz .LBB0_1092
	s_cmp_eq_u32 s13, 15
	v_cmp_gt_i32_e32 vcc, 16, v66
	s_cselect_b64 s[6:7], -1, 0
	s_and_b64 s[8:9], s[34:35], vcc
	s_and_b64 s[8:9], s[6:7], s[8:9]
	s_and_saveexec_b64 s[6:7], s[8:9]
	s_cbranch_execz .LBB0_1101
	v_ashrrev_i32_e32 v0, 2, v66
	v_add_u32_e32 v2, s11, v0
	v_ashrrev_i32_e32 v3, 31, v2
	v_lshlrev_b64 v[2:3], 6, v[2:3]
	v_lshl_add_u64 v[2:3], s[4:5], 0, v[2:3]
	s_lshl_b32 s4, s10, 12
	s_load_dwordx2 s[8:9], s[90:91], 0xb8
	s_add_i32 s16, s4, 0x800000
	s_lshl_b64 s[4:5], s[16:17], 1
	v_ashrrev_i32_e32 v1, 31, v0
	s_add_u32 s2, s2, s4
	v_lshlrev_b64 v[6:7], 11, v[0:1]
	v_or_b32_e32 v1, s12, v54
	s_addc_u32 s3, s3, s5
	v_lshlrev_b32_e32 v16, 6, v1
	v_lshl_add_u64 v[6:7], s[2:3], 0, v[6:7]
	s_mov_b64 s[2:3], 0x31700008
	s_waitcnt lgkmcnt(0)
	v_lshl_add_u64 v[4:5], v[16:17], 2, s[8:9]
	v_lshl_add_u64 v[6:7], v[6:7], 0, s[2:3]
	v_mov_b32_e32 v1, 0
	s_mov_b32 s16, 0

; __device__ __forceinline__ void ssc_unit(const Ctx& c, int l, int sb, int ksp) {
;     ...
;         for (int i = 0; i < 4; ++i) {
;             const int s0 = ksp * 1024 + (c.wave + 8 * i) * 32;
;             const int page = ptab[s0 >> 7];
;             const float* kp = c.f(I_CKI) + (((size_t)l * NPOOL + page) * 128 + (s0 & 127) + n) * 64 + 8 * hf;
;             f32x16 acc;
; #pragma unroll
;             for (int v = 0; v < 16; ++v) acc[v] = 0.f;
; #pragma unroll
;             for (int ks = 0; ks < 4; ++ks) {
;                 const f32x4 k0 = *(const f32x4*)(kp + 16 * ks), k1 = *(const f32x4*)(kp + 16 * ks + 4);
;                 acc = __builtin_amdgcn_mfma_f32_32x32x16_bf16(Af[ks], pack8(k0, k1), acc, 0, 0, 0);
;             }
;             float sc = 0.f;
; #pragma unroll
;             for (int v = 0; v < 16; ++v) sc += wq[v] * fmaxf(acc[v], 0.f);
;             SCS[(size_t)(2 * pr + hf) * SCS_LD + s0 + n] = sc;
;         }
;     }
;     if (ksp == 15 && c.wave == 0 && lane < 16) {
.LBB0_2616:
	s_add_i32 s8, s17, s18
	s_ashr_i32 s20, s8, 7
	s_ashr_i32 s21, s20, 31
	s_lshl_b64 s[20:21], s[20:21], 2
	s_add_u32 s20, s14, s20
	s_addc_u32 s21, s16, s21
	global_load_dword v0, v17, s[20:21]
	s_mov_b32 s9, 0x2800000
	s_mov_b64 s[20:21], 0x2800000
	s_addk_i32 s18, 0x100
	s_waitcnt vmcnt(0)
	v_ashrrev_i32_e32 v1, 31, v0
	v_lshlrev_b64 v[0:1], 15, v[0:1]
	v_lshl_add_u64 v[76:77], v[38:39], 0, v[0:1]
	v_add_co_u32_e32 v78, vcc, s9, v76
	v_lshl_add_u64 v[4:5], v[76:77], 0, s[20:21]
	s_nop 0
	v_addc_co_u32_e32 v79, vcc, 0, v77, vcc
	global_load_dwordx4 v[0:3], v[78:79], off
	global_load_dwordx4 v[4:7], v[78:79], off offset:16
	global_load_dwordx4 v[68:71], v[78:79], off offset:64
	global_load_dwordx4 v[72:75], v[78:79], off offset:80
	global_load_dwordx4 v[80:83], v[78:79], off offset:128
	global_load_dwordx4 v[84:87], v[78:79], off offset:144
	global_load_dwordx4 v[88:91], v[78:79], off offset:192
	global_load_dwordx4 v[92:95], v[78:79], off offset:208
	s_ashr_i32 s9, s8, 31
	s_cmpk_eq_i32 s18, 0x400
	s_waitcnt vmcnt(6)
	v_cvt_pk_bf16_f32 v0, v0, v1
	v_cvt_pk_bf16_f32 v1, v2, v3
	v_cvt_pk_bf16_f32 v2, v4, v5
	v_cvt_pk_bf16_f32 v3, v6, v7
	s_nop 1
	v_mfma_f32_32x32x16_bf16 v[0:15], v[18:21], v[0:3], 0
	s_waitcnt vmcnt(4)
	v_cvt_pk_bf16_f32 v68, v68, v69
	v_cvt_pk_bf16_f32 v69, v70, v71
	v_cvt_pk_bf16_f32 v70, v72, v73
	v_cvt_pk_bf16_f32 v71, v74, v75
	s_nop 1
	v_mfma_f32_32x32x16_bf16 v[0:15], v[22:25], v[68:71], v[0:15]
	s_waitcnt vmcnt(2)
	v_cvt_pk_bf16_f32 v80, v80, v81
	v_cvt_pk_bf16_f32 v81, v82, v83
	v_cvt_pk_bf16_f32 v82, v84, v85
	v_cvt_pk_bf16_f32 v83, v86, v87
	s_nop 1
	v_mfma_f32_32x32x16_bf16 v[0:15], v[26:29], v[80:83], v[0:15]
	s_waitcnt vmcnt(0)
	v_cvt_pk_bf16_f32 v88, v88, v89
	v_cvt_pk_bf16_f32 v89, v90, v91
	v_cvt_pk_bf16_f32 v90, v92, v93
	v_cvt_pk_bf16_f32 v91, v94, v95
	s_nop 1
	v_mfma_f32_32x32x16_bf16 v[0:15], v[30:33], v[88:91], v[0:15]
	s_nop 11
	v_max_f32_e32 v0, v0, v0
	v_max_f32_e32 v0, 0, v0
	v_fma_f32 v61, v16, v0, 0
	v_max_f32_e32 v0, v1, v1
	v_max_f32_e32 v0, 0, v0
	v_fmac_f32_e32 v61, v58, v0
	v_max_f32_e32 v0, v2, v2
	v_max_f32_e32 v0, 0, v0
	v_fmac_f32_e32 v61, v59, v0
	v_max_f32_e32 v0, v3, v3
	v_max_f32_e32 v0, 0, v0
	v_fmac_f32_e32 v61, v60, v0
	v_max_f32_e32 v0, v4, v4
	v_max_f32_e32 v1, v5, v5
	v_max_f32_e32 v0, 0, v0
	v_max_f32_e32 v1, 0, v1
	v_pk_mul_f32 v[0:1], v[40:41], v[0:1]
	s_nop 0
	v_add_f32_e32 v0, v0, v61
	v_add_f32_e32 v2, v1, v0
	v_max_f32_e32 v0, v6, v6
	v_max_f32_e32 v1, v7, v7
	v_max_f32_e32 v0, 0, v0
	v_max_f32_e32 v1, 0, v1
	v_pk_mul_f32 v[0:1], v[42:43], v[0:1]
	s_nop 0
	v_add_f32_e32 v0, v0, v2
	v_add_f32_e32 v2, v1, v0
	v_max_f32_e32 v0, v8, v8
	v_max_f32_e32 v1, v9, v9
	v_max_f32_e32 v0, 0, v0
	v_max_f32_e32 v1, 0, v1
	v_pk_mul_f32 v[0:1], v[44:45], v[0:1]
	s_nop 0
	v_add_f32_e32 v0, v0, v2
	v_add_f32_e32 v2, v1, v0
	v_max_f32_e32 v0, v10, v10
	v_max_f32_e32 v1, v11, v11
	v_max_f32_e32 v0, 0, v0
	v_max_f32_e32 v1, 0, v1
	v_pk_mul_f32 v[0:1], v[46:47], v[0:1]
	s_nop 0
	v_add_f32_e32 v0, v0, v2
	v_add_f32_e32 v2, v1, v0
	v_max_f32_e32 v0, v12, v12
	v_max_f32_e32 v1, v13, v13
	v_max_f32_e32 v0, 0, v0
	v_max_f32_e32 v1, 0, v1
	v_pk_mul_f32 v[0:1], v[48:49], v[0:1]
	s_nop 0
	v_add_f32_e32 v0, v0, v2
	v_add_f32_e32 v2, v1, v0
	v_max_f32_e32 v0, v14, v14
	v_max_f32_e32 v1, v15, v15
	v_max_f32_e32 v0, 0, v0
	v_max_f32_e32 v1, 0, v1
	v_pk_mul_f32 v[0:1], v[50:51], v[0:1]
	s_nop 0
	v_add_f32_e32 v0, v0, v2
	v_add_f32_e32 v2, v1, v0
	v_lshl_add_u64 v[0:1], s[8:9], 2, v[52:53]
	global_store_dword v[0:1], v2, off
	s_cbranch_scc0 .LBB0_2616
	s_mov_b32 s18, 2
	s_mov_b64 s[8:9], 0
	s_and_b64 vcc, exec, s[6:7]
	s_cbranch_vccz .LBB0_2615
	s_cmp_eq_u32 s13, 15
	v_cmp_gt_i32_e32 vcc, 16, v66
	s_cselect_b64 s[6:7], -1, 0
	s_and_b64 s[8:9], s[30:31], vcc
	s_and_b64 s[8:9], s[6:7], s[8:9]
	s_and_saveexec_b64 s[6:7], s[8:9]
	s_mov_b32 s18, s24
	s_cbranch_execz .LBB0_2624
	v_ashrrev_i32_e32 v0, 2, v66
	v_add_u32_e32 v2, s11, v0
	v_ashrrev_i32_e32 v3, 31, v2
	v_lshlrev_b64 v[2:3], 6, v[2:3]
	v_lshl_add_u64 v[2:3], s[4:5], 0, v[2:3]
	s_lshl_b32 s4, s10, 12
	s_load_dwordx2 s[8:9], s[90:91], 0xb8
	s_add_i32 s14, s4, 0x800000
	s_add_i32 s12, s12, 32
	s_lshl_b64 s[4:5], s[14:15], 1
	v_ashrrev_i32_e32 v1, 31, v0
	s_add_u32 s2, s2, s4
	v_lshlrev_b64 v[6:7], 11, v[0:1]
	v_or_b32_e32 v1, s12, v54
	s_addc_u32 s3, s3, s5
	v_lshlrev_b32_e32 v16, 6, v1
	v_lshl_add_u64 v[6:7], s[2:3], 0, v[6:7]
	s_mov_b64 s[2:3], 0x31700008
	s_waitcnt lgkmcnt(0)
	v_lshl_add_u64 v[4:5], v[16:17], 2, s[8:9]
	v_lshl_add_u64 v[6:7], v[6:7], 0, s[2:3]
	v_mov_b32_e32 v1, 0
	s_mov_b32 s14, 0
